# v24 + attn0 fast path: step loads deferred past QK, staging regs v[166:181] hold 4 rolling K fragments, QK MFMAs spread through the row-max stream
# baseline (speedup 1.0000x reference)
;     ...
;             } else if (k0 + 63 > qw0) {
;     ...
;             const int kt = j0 + kk;
;             if (DEEP) { if (kk + 3 < ntl) gload(rg_ld, ck_ld, kt + 3); } else { if (kk + 2 < ntl) gload(rg_ld, ck_ld, kt + 2); }
;             if (MODE == 2 && kk + 2 < ntl) wnext2 = mrow[kt + 2];
;             if (kk + 1 < ntl && (kt + 1) * 64 <= qw0 + 31) qk(s_nxt, mi_nxt, (kk + 1) % 3);
;             if (kt * 64 <= qw0 + 31) softmax_pv(s_cur, mi_cur, kt, kk % 3);
.LBB0_1259:
	s_add_i32 s97, s16, 2
	s_cmp_lt_i32 s97, s96
	s_cselect_b64 s[10:11], -1, 0
	s_cmp_ge_i32 s97, s96
	s_cselect_b64 s[46:47], -1, 0
	s_add_i32 s61, s16, 1
	s_cmp_lt_i32 s61, s96
	s_cselect_b64 s[98:99], -1, 0
	s_and_b64 s[98:99], s[98:99], s[10:11]
	s_sub_i32 s61, s58, 30
	v_cmp_le_i32_e64 s[100:101], s61, v186
	s_nop 0
	s_and_b64 s[98:99], s[98:99], s[100:101]
	s_sub_i32 s61, s58, 63
	v_cmp_le_i32_e64 s[100:101], s61, v197
	s_nop 0
	s_and_b64 s[98:99], s[98:99], s[100:101]
	v_cmp_gt_i32_e64 s[100:101], s58, v186
	s_nop 0
	s_andn2_b64 s[98:99], s[98:99], s[100:101]
	s_cmp_eq_u64 s[98:99], exec
	s_cbranch_scc1 .Lh0a_fast
	s_and_b64 vcc, exec, s[46:47]
	s_cbranch_vccnz .LBB0_1261
	v_lshl_add_u64 v[4:5], v[202:203], 0, v[182:183]
	v_add_co_u32_e32 v4, vcc, 0x72c0000, v4
	s_nop 1
	v_addc_co_u32_e32 v5, vcc, 0, v5, vcc
	global_load_dwordx4 v[166:169], v[4:5], off offset:1024
	global_load_dwordx4 v[170:173], v[4:5], off offset:1152
	v_lshl_add_u64 v[4:5], v[204:205], 0, v[182:183]
	v_add_co_u32_e32 v8, vcc, 0x15200000, v4
	s_nop 1
	v_addc_co_u32_e32 v9, vcc, 0, v5, vcc
	v_add_co_u32_e32 v4, vcc, 0x15300000, v4
	s_nop 1
	v_addc_co_u32_e32 v5, vcc, 0, v5, vcc
	global_load_dwordx4 v[174:177], v[8:9], off offset:256
	global_load_dwordx4 v[178:181], v[4:5], off offset:256

;     ...
;             const int kt = j0 + kk;
;             if (DEEP) { if (kk + 3 < ntl) gload(rg_ld, ck_ld, kt + 3); } else { if (kk + 2 < ntl) gload(rg_ld, ck_ld, kt + 2); }
;             if (MODE == 2 && kk + 2 < ntl) wnext2 = mrow[kt + 2];
;             if (kk + 1 < ntl && (kt + 1) * 64 <= qw0 + 31) qk(s_nxt, mi_nxt, (kk + 1) % 3);
;             if (kt * 64 <= qw0 + 31) softmax_pv(s_cur, mi_cur, kt, kk % 3);
;             if (MODE == 2) { wcur = wnext; wnext = wnext2; }
;             if (kk + 2 < ntl) lstore(rg_st, ck_st, (kk + 2) % 3);
;             __syncthreads();
.LBB0_1276:
	s_cmp_ge_i32 s17, s96
	s_waitcnt lgkmcnt(0)
	s_barrier
	s_cbranch_scc1 .LBB0_1295
	s_add_i32 s1, s16, 3
	s_cmp_lt_i32 s1, s96
	s_cselect_b64 s[48:49], -1, 0
	s_cmp_lt_i32 s97, s96
	s_cselect_b64 s[98:99], -1, 0
	s_and_b64 s[98:99], s[98:99], s[48:49]
	s_add_i32 s61, s58, 34
	v_cmp_le_i32_e64 s[100:101], s61, v186
	s_nop 0
	s_and_b64 s[98:99], s[98:99], s[100:101]
	s_add_i32 s61, s58, 1
	v_cmp_le_i32_e64 s[100:101], s61, v197
	s_nop 0
	s_and_b64 s[98:99], s[98:99], s[100:101]
	s_add_i32 s61, s58, 64
	v_cmp_gt_i32_e64 s[100:101], s61, v186
	s_nop 0
	s_andn2_b64 s[98:99], s[98:99], s[100:101]
	s_cmp_eq_u64 s[98:99], exec
	s_cbranch_scc1 .Lh0b_fast
	s_cmp_ge_i32 s1, s96
	s_cbranch_scc1 .LBB0_1279
	v_lshl_add_u64 v[4:5], v[202:203], 0, v[182:183]
	v_add_co_u32_e32 v4, vcc, 0x7320000, v4
	s_nop 1
	v_addc_co_u32_e32 v5, vcc, 0, v5, vcc
	global_load_dwordx4 v[166:169], v[4:5], off offset:1024
	global_load_dwordx4 v[170:173], v[4:5], off offset:1152
	v_lshl_add_u64 v[4:5], v[204:205], 0, v[182:183]
	v_add_co_u32_e32 v8, vcc, 0x15200000, v4
	s_nop 1
	v_addc_co_u32_e32 v9, vcc, 0, v5, vcc
	v_add_co_u32_e32 v4, vcc, 0x15300000, v4
	s_nop 1
	v_addc_co_u32_e32 v5, vcc, 0, v5, vcc
	global_load_dwordx4 v[174:177], v[8:9], off offset:384
	global_load_dwordx4 v[178:181], v[4:5], off offset:384

; #define MFMA32(a, b, c) __builtin_amdgcn_mfma_f32_32x32x16_bf16((a), (b), (c), 0, 0, 0)
; DI unsigned pk_bf16(float a, float b) { f32x2 v = {a, b}; bf2_t r = __builtin_convertvector(v, bf2_t); return __builtin_bit_cast(unsigned, r); }
; DI float xhalf_max(float v) { const auto r = __builtin_amdgcn_permlane32_swap(__float_as_uint(v), __float_as_uint(v), false, false); return fmaxf(__uint_as_float(r[0]), __uint_as_float(r[1])); }
;     ...
;         auto qk = [&](f32x16 (&s)[2], float& mi, int stg) {
;             const unsigned char* kb_ = lds + stg * STG + koff;
;             const unsigned mb = pk_bf16((m > -1e29f) ? -m : 0.f, 0.f) & 0xffffu;
;             mi = -__uint_as_float(mb << 16);
;             u32x4 qxw; qxw.x = hh ? 0u : mb; qxw.y = 0u; qxw.z = 0u; qxw.w = 0u;
;             u32x4 kxw; kxw.x = hh ? 0u : 0x3f80u; kxw.y = 0u; kxw.z = 0u; kxw.w = 0u;
;             const bf16x8 qx = __builtin_bit_cast(bf16x8, qxw), kx = __builtin_bit_cast(bf16x8, kxw);
;             f32x16 zero;
; #pragma unroll
;             for (int i = 0; i < 16; ++i) zero[i] = 0.f;
; #pragma unroll
;             for (int blk = 0; blk < 2; ++blk) {
;                 s[blk] = MFMA32(kx, qx, zero);
; #pragma unroll
;                 for (int ks = 0; ks < 4; ++ks) {
;                     const bf16x8 kf = *(const bf16x8*)(kb_ + blk * 4608 + ks * 32);
;                     s[blk] = MFMA32(kf, qf[ks], s[blk]);
;                 }
;             }
;         };
;     ...
;             float mx = s[0][0];
; #pragma unroll
;             for (int i = 1; i < 16; ++i) mx = fmaxf(mx, s[0][i]);
; #pragma unroll
;             for (int i = 0; i < 16; ++i) mx = fmaxf(mx, s[1][i]);
;             mx = xhalf_max(mx);
;             const float mabs = mi + mx;
;             const bool up = mabs > m + 8.0f;
;             const float mn = up ? __uint_as_float(pk_bf16(mabs, 0.f) << 16) : m;
.Lh0a_fast:
	s_mul_hi_u32 s0, s45, 0xaaaaaaab
	s_lshr_b32 s60, s0, 1
	s_add_i32 s17, s16, 1
	s_mul_i32 s60, s60, 0x1a400
	s_mov_b64 s[12:13], exec
	v_subrev_u32_e32 v4, s60, v236
	v_add3_u32 v16, v235, s56, v4
	ds_read_b128 v[166:169], v16 offset:35840
	ds_read_b128 v[170:173], v16 offset:35872
	ds_read_b128 v[174:177], v16 offset:35904
	ds_read_b128 v[178:181], v16 offset:35936
	v_cmp_lt_f32_e64 s[8:9], s90, v207
	s_mov_b64 vcc, s[2:3]
	v_mov_b32_e32 v4, v3
	v_cndmask_b32_e64 v2, 0, -v207, s[8:9]
	v_cvt_pk_bf16_f32 v7, v2, 0
	v_cndmask_b32_sdwa v2, v3, v7, vcc dst_sel:DWORD dst_unused:UNUSED_PAD src0_sel:DWORD src1_sel:WORD_0
	v_mov_b32_e32 v5, v3
	v_lshlrev_b32_e32 v7, 16, v7
	v_xor_b32_e32 v208, 0x80000000, v7
	v_mfma_f32_32x32x16_bf16 v[18:33], v[146:149], v[2:5], 0
	v_max_f32_e32 v2, v131, v131
	v_max_f32_e32 v4, v130, v130
	v_max_f32_e32 v2, v4, v2
	s_waitcnt lgkmcnt(3)
	v_mfma_f32_32x32x16_bf16 v[34:49], v[166:169], v[150:153], v[18:33]
	ds_read_b128 v[166:169], v16 offset:40448
	v_max3_f32 v2, v2, v132, v133
	v_max3_f32 v2, v2, v134, v135
	v_max3_f32 v2, v2, v136, v137
	v_max3_f32 v2, v2, v138, v139
	s_waitcnt lgkmcnt(3)
	v_mfma_f32_32x32x16_bf16 v[34:49], v[170:173], v[158:161], v[34:49]
	ds_read_b128 v[170:173], v16 offset:40480
	v_max3_f32 v2, v2, v140, v141
	v_max3_f32 v2, v2, v142, v143
	v_max3_f32 v2, v2, v144, v145
	s_waitcnt lgkmcnt(3)
	v_mfma_f32_32x32x16_bf16 v[34:49], v[174:177], v[162:165], v[34:49]
	ds_read_b128 v[174:177], v16 offset:40512
	v_max3_f32 v2, v2, v114, v115
	v_max3_f32 v2, v2, v116, v117
	v_max3_f32 v2, v2, v118, v119
	v_max3_f32 v2, v2, v120, v121
	s_waitcnt lgkmcnt(3)
	v_mfma_f32_32x32x16_bf16 v[34:49], v[178:181], v[154:157], v[34:49]
	ds_read_b128 v[178:181], v16 offset:40544
	v_max3_f32 v2, v2, v122, v123
	v_max3_f32 v2, v2, v124, v125
	v_max3_f32 v2, v2, v126, v127
	s_waitcnt lgkmcnt(3)
	v_mfma_f32_32x32x16_bf16 v[18:33], v[166:169], v[150:153], v[18:33]
	v_max3_f32 v2, v2, v128, v129
	v_mov_b32_e32 v4, v2
	s_nop 1
	v_permlane32_swap_b32_e32 v2, v4
	s_waitcnt lgkmcnt(2)
	v_mfma_f32_32x32x16_bf16 v[18:33], v[170:173], v[158:161], v[18:33]
	v_max_f32_e32 v4, v4, v4
	v_max_f32_e32 v2, v2, v2
	v_max_f32_e32 v198, v2, v4
	s_waitcnt lgkmcnt(1)
	v_mfma_f32_32x32x16_bf16 v[18:33], v[174:177], v[162:165], v[18:33]
	v_pk_add_f32 v[4:5], v[206:207], v[198:199]
	s_nop 0
	v_cvt_pk_bf16_f32 v2, v4, 0
	v_lshlrev_b32_e32 v2, 16, v2
	s_waitcnt lgkmcnt(0)
	v_mfma_f32_32x32x16_bf16 v[18:33], v[178:181], v[154:157], v[18:33]
	v_cmp_gt_f32_e64 s[8:9], v4, v5
	s_nop 1
	v_cndmask_b32_e64 v4, v207, v2, s[8:9]
	v_lshl_add_u64 v[10:11], v[202:203], 0, v[182:183]
	v_add_co_u32_e32 v10, vcc, 0x72c0000, v10
	s_nop 1
	v_addc_co_u32_e32 v11, vcc, 0, v11, vcc
	global_load_dwordx4 v[166:169], v[10:11], off offset:1024
	global_load_dwordx4 v[170:173], v[10:11], off offset:1152
	v_lshl_add_u64 v[10:11], v[204:205], 0, v[182:183]
	v_add_co_u32_e32 v12, vcc, 0x15200000, v10
	s_nop 1
	v_addc_co_u32_e32 v13, vcc, 0, v11, vcc
	v_add_co_u32_e32 v10, vcc, 0x15300000, v10
	s_nop 1
	v_addc_co_u32_e32 v11, vcc, 0, v11, vcc
	global_load_dwordx4 v[174:177], v[12:13], off offset:256
	global_load_dwordx4 v[178:181], v[10:11], off offset:256
	v_sub_f32_e32 v2, v4, v206
	v_cmp_neq_f32_e32 vcc, 0, v2
	s_cbranch_vccz .LBB0_1273
	s_branch .Lh0a_cont
.Lh0b_fast:
	s_mov_b64 s[50:51], exec
	v_add_u32_e32 v16, s56, v235
	v_subrev_u32_e32 v7, s0, v244
	v_add_u32_e32 v7, v16, v7
	ds_read_b128 v[166:169], v7
	v_subrev_u32_e32 v7, s0, v243
	v_add_u32_e32 v7, v16, v7
	ds_read_b128 v[170:173], v7
	v_subrev_u32_e32 v7, s0, v242
	v_add_u32_e32 v7, v16, v7
	ds_read_b128 v[174:177], v7
	v_subrev_u32_e32 v7, s0, v241
	v_add_u32_e32 v7, v16, v7
	ds_read_b128 v[178:181], v7
	v_subrev_u32_e32 v7, s0, v240
	v_add_u32_e32 v16, v16, v7
	v_cmp_lt_f32_e32 vcc, s90, v207
	v_mov_b32_e32 v4, v3
	v_mov_b32_e32 v5, v3
	v_cndmask_b32_e64 v2, 0, -v207, vcc
	v_cvt_pk_bf16_f32 v7, v2, 0
	v_and_b32_e32 v2, 0xffff, v7
	v_lshlrev_b32_e32 v7, 16, v7
	v_cndmask_b32_e64 v2, 0, v2, s[2:3]
	v_xor_b32_e32 v206, 0x80000000, v7
	s_nop 0
	v_mfma_f32_32x32x16_bf16 v[114:129], v[146:149], v[2:5], 0
	v_max_f32_e32 v2, v35, v35
	v_max_f32_e32 v4, v34, v34
	v_max_f32_e32 v2, v4, v2
	v_max3_f32 v2, v2, v36, v37
	s_waitcnt lgkmcnt(3)
	v_mfma_f32_32x32x16_bf16 v[130:145], v[166:169], v[150:153], v[114:129]
	ds_read_b128 v[166:169], v16
	v_max3_f32 v2, v2, v38, v39
	v_max3_f32 v2, v2, v40, v41
	v_max3_f32 v2, v2, v42, v43
	s_waitcnt lgkmcnt(3)
	v_mfma_f32_32x32x16_bf16 v[130:145], v[170:173], v[158:161], v[130:145]
	ds_read_b128 v[170:173], v16 offset:32
	v_max3_f32 v2, v2, v44, v45
	v_max3_f32 v2, v2, v46, v47
	v_max3_f32 v2, v2, v48, v49
	v_max3_f32 v2, v2, v18, v19
	s_waitcnt lgkmcnt(3)
	v_mfma_f32_32x32x16_bf16 v[130:145], v[174:177], v[162:165], v[130:145]
	ds_read_b128 v[174:177], v16 offset:64
	v_max3_f32 v2, v2, v20, v21
	v_max3_f32 v2, v2, v22, v23
	v_max3_f32 v2, v2, v24, v25
	s_waitcnt lgkmcnt(3)
	v_mfma_f32_32x32x16_bf16 v[130:145], v[178:181], v[154:157], v[130:145]
	ds_read_b128 v[178:181], v16 offset:96
	v_max3_f32 v2, v2, v26, v27
	v_max3_f32 v2, v2, v28, v29
	v_max3_f32 v2, v2, v30, v31
	v_max3_f32 v2, v2, v32, v33
	s_waitcnt lgkmcnt(3)
	v_mfma_f32_32x32x16_bf16 v[114:129], v[166:169], v[150:153], v[114:129]
	v_mov_b32_e32 v4, v2
	s_nop 1
	v_permlane32_swap_b32_e32 v2, v4
	s_waitcnt lgkmcnt(2)
	v_mfma_f32_32x32x16_bf16 v[114:129], v[170:173], v[158:161], v[114:129]
	v_max_f32_e32 v4, v4, v4
	v_max_f32_e32 v2, v2, v2
	v_max_f32_e32 v198, v2, v4
	v_mov_b32_e32 v209, v207
	s_waitcnt lgkmcnt(1)
	v_mfma_f32_32x32x16_bf16 v[114:129], v[174:177], v[162:165], v[114:129]
	v_pk_add_f32 v[4:5], v[208:209], v[198:199]
	s_nop 0
	v_cvt_pk_bf16_f32 v2, v4, 0
	s_waitcnt lgkmcnt(0)
	v_mfma_f32_32x32x16_bf16 v[114:129], v[178:181], v[154:157], v[114:129]
	v_lshlrev_b32_e32 v2, 16, v2
	v_cmp_gt_f32_e64 s[8:9], v4, v5
	s_nop 1
	v_cndmask_b32_e64 v4, v207, v2, s[8:9]
	v_lshl_add_u64 v[10:11], v[202:203], 0, v[182:183]
	v_add_co_u32_e32 v10, vcc, 0x7320000, v10
	s_nop 1
	v_addc_co_u32_e32 v11, vcc, 0, v11, vcc
	global_load_dwordx4 v[166:169], v[10:11], off offset:1024
	global_load_dwordx4 v[170:173], v[10:11], off offset:1152
	v_lshl_add_u64 v[10:11], v[204:205], 0, v[182:183]
	v_add_co_u32_e32 v12, vcc, 0x15200000, v10
	s_nop 1
	v_addc_co_u32_e32 v13, vcc, 0, v11, vcc
	v_add_co_u32_e32 v10, vcc, 0x15300000, v10
	s_nop 1
	v_addc_co_u32_e32 v11, vcc, 0, v11, vcc
	global_load_dwordx4 v[174:177], v[12:13], off offset:384
	global_load_dwordx4 v[178:181], v[10:11], off offset:384
	v_sub_f32_e32 v2, v4, v208
	v_cmp_neq_f32_e32 vcc, 0, v2
	s_cbranch_vccz .LBB0_1291
	s_branch .Lh0b_cont
